# v7: + queue loop heads wait lgkmcnt only (store acks overlap next item)
# speedup vs baseline: 1.0392x; 1.0036x over previous
; #define LAS __attribute__((address_space(3)))
; __device__ __forceinline__ int otid(int wv) { int ln; asm volatile("v_mbcnt_lo_u32_b32 %0, -1, 0\n\tv_mbcnt_hi_u32_b32 %0, -1, %0" : "=v"(ln)); return wv * 64 + ln; }
; __global__ void __launch_bounds__(512, 2) hybrid_fwd(Params p_unused) {
;     ...
;         { const int nNA = need_ctx ? 864 : 768, total = nNA + 1152;
;           unsigned nxt_it = 0;
;           const bool t0 = (otid(wv) == 0);
;           if (t0) { const Params p = ldp(); nxt_it = atomicAdd((unsigned*)(p.ws + OFF_CTR) + l, 1u); }
;           for (;;) {
;               __syncthreads();
;               if (t0) *(LAS unsigned*)(lds + QWORD_OFF) = nxt_it;
.LBB0_664:
	s_or_b64 exec, exec, s[6:7]
	s_mov_b32 s4, s72
	s_lshl_b32 s56, s72, 6
	v_writelane_b32 v255, s4, 22
	s_or_b32 s0, s1, 0x480
	s_lshl_b32 s94, s72, 1
	s_lshl_b64 s[48:49], s[56:57], 2
	v_writelane_b32 v255, s5, 23
	s_waitcnt vmcnt(0)
	s_branch .LBB0_667

; #define LAS __attribute__((address_space(3)))
; __global__ void __launch_bounds__(512, 2) hybrid_fwd(Params p_unused) {
;     ...
;           for (;;) {
;               __syncthreads();
;               if (t0) *(LAS unsigned*)(lds + QWORD_OFF) = nxt_it;
;               __syncthreads();
;               const int it = (int)*(LAS unsigned*)(lds + QWORD_OFF);
;               if (it >= total) break;
;               if (t0) { const Params p = ldp(); nxt_it = atomicAdd((unsigned*)(p.ws + OFF_CTR) + l, 1u); }
.LBB0_667:
	s_waitcnt lgkmcnt(0)
	s_barrier
	s_and_saveexec_b64 s[4:5], s[10:11]
	v_mov_b32_e32 v0, s76
	ds_write_b32 v0, v109
	s_or_b64 exec, exec, s[4:5]
	v_mov_b32_e32 v0, s76
	s_waitcnt lgkmcnt(0)
	s_barrier
	ds_read_b32 v0, v0
	s_waitcnt lgkmcnt(0)
	v_cmp_le_i32_e64 s[12:13], s0, v0
	v_readfirstlane_b32 s3, v0
	s_and_b64 vcc, exec, s[12:13]
	s_cbranch_vccnz .LBB0_666
	s_and_saveexec_b64 s[4:5], s[10:11]
	s_cbranch_execz .LBB0_673
	s_mov_b64 s[6:7], s[90:91]
	s_load_dwordx2 s[6:7], s[6:7], 0xa8
	s_waitcnt lgkmcnt(0)
	v_lshl_add_u64 v[2:3], v[130:131], 2, s[6:7]
	v_add_co_u32_e32 v2, vcc, 0xfab9000, v2
	s_nop 1
	v_addc_co_u32_e32 v3, vcc, 0, v3, vcc
	global_atomic_add v109, v[2:3], v230, off offset:2048 sc0
	s_or_b64 exec, exec, s[4:5]
	s_cmp_ge_i32 s3, s1
	s_mov_b64 s[4:5], -1
	s_cbranch_scc1 .LBB0_674

; #define LAS __attribute__((address_space(3)))
; __device__ __forceinline__ int otid(int wv) { int ln; asm volatile("v_mbcnt_lo_u32_b32 %0, -1, 0\n\tv_mbcnt_hi_u32_b32 %0, -1, %0" : "=v"(ln)); return wv * 64 + ln; }
; __global__ void __launch_bounds__(512, 2) hybrid_fwd(Params p_unused) {
;     ...
;         { const int nch = need_ctx ? 36 : 32, nit = 8 * nch * 4;
;           unsigned nxt_it = 0; const bool t0 = (otid(wv) == 0);
;           if (t0) { const Params p = ldp(); nxt_it = atomicAdd((unsigned*)(p.ws + OFF_CTR) + 2 + l, 1u); }
;           for (;;) {
;               __syncthreads();
;               if (t0) *(LAS unsigned*)(lds + QWORD_OFF) = nxt_it;
.LBB0_953:
	s_or_b64 exec, exec, s[4:5]
	v_readlane_b32 s0, v255, 18
	v_readlane_b32 s1, v255, 19
	s_and_b64 s[0:1], s[0:1], exec
	s_cselect_b32 s1, 36, 32
	s_lshl_b32 s0, s1, 2
	v_cvt_f32_ubyte0_e32 v0, s0
	v_rcp_iflag_f32_e32 v0, v0
	s_sub_i32 s3, 0, s0
	s_mul_i32 s56, s72, 0x60
	s_lshl_b32 s1, s1, 5
	v_mul_f32_e32 v0, 0x4f7ffffe, v0
	v_cvt_u32_f32_e32 v0, v0
	s_lshl_b64 s[8:9], s[56:57], 2
	v_readlane_b32 s42, v254, 55
	s_movk_i32 s43, 0x100
	v_readfirstlane_b32 s4, v0
	s_mul_i32 s3, s3, s4
	s_mul_hi_u32 s3, s4, s3
	s_add_i32 s29, s4, s3
	s_movk_i32 s46, 0x300
	s_movk_i32 s47, 0x480
	s_movk_i32 s48, 0x60
	s_movk_i32 s49, 0x5ff
	s_movk_i32 s50, 0x800
	s_movk_i32 s51, 0x56
	s_movk_i32 s52, 0x180
	s_mov_b32 s53, 0x38e38e39
	s_movk_i32 s60, 0x2aab
	s_movk_i32 s61, 0x240
	s_movk_i32 s64, 0x184
	s_waitcnt vmcnt(0)
	s_branch .LBB0_956

; #define LAS __attribute__((address_space(3)))
; __global__ void __launch_bounds__(512, 2) hybrid_fwd(Params p_unused) {
;     ...
;           for (;;) {
;               __syncthreads();
;               if (t0) *(LAS unsigned*)(lds + QWORD_OFF) = nxt_it;
;               __syncthreads();
;               const int it = (int)*(LAS unsigned*)(lds + QWORD_OFF);
;               if (it >= nit) break;
;               if (t0) { const Params p = ldp(); nxt_it = atomicAdd((unsigned*)(p.ws + OFF_CTR) + 2 + l, 1u); }
.LBB0_956:
	s_waitcnt lgkmcnt(0)
	s_barrier
	s_and_saveexec_b64 s[4:5], s[10:11]
	v_mov_b32_e32 v0, s76
	ds_write_b32 v0, v80
	s_or_b64 exec, exec, s[4:5]
	v_mov_b32_e32 v0, s76
	s_waitcnt lgkmcnt(0)
	s_barrier
	ds_read_b32 v0, v0
	s_waitcnt lgkmcnt(0)
	v_cmp_le_i32_e64 s[12:13], s1, v0
	v_readfirstlane_b32 s3, v0
	s_and_b64 vcc, exec, s[12:13]
	s_cbranch_vccnz .LBB0_955
	s_and_saveexec_b64 s[4:5], s[10:11]
	s_cbranch_execz .LBB0_961
	s_mov_b64 s[6:7], s[90:91]
	s_load_dwordx2 s[6:7], s[6:7], 0xa8
	s_waitcnt lgkmcnt(0)
	v_lshl_add_u64 v[2:3], v[130:131], 2, s[6:7]
	v_add_co_u32_e32 v2, vcc, 0xfab9000, v2
	s_nop 1
	v_addc_co_u32_e32 v3, vcc, 0, v3, vcc
	global_atomic_add v80, v[2:3], v230, off offset:2056 sc0
